# GEMM2 partial exchange kept inside one XCD: plain (L2-resident) partial stores when every workgroup's XCC id equals blockIdx&7 (checked at the first grid barrier), write-through otherwise
# baseline (speedup 1.0000x reference)
.LBB0_94:
	s_waitcnt lgkmcnt(0)
	s_mov_b32 s2, s91
	s_mov_b32 s4, 0
	s_waitcnt vmcnt(0)
	s_mov_b32 s5, 0
	v_or_b32_e32 v0, s2, v230
	v_cmp_eq_u32_e32 vcc, 0, v0
	s_barrier
	s_and_saveexec_b64 s[2:3], vcc
	s_cbranch_execz .LBB0_138
	v_writelane_b32 v2, s4, 1
	v_writelane_b32 v2, s5, 2
	v_writelane_b32 v2, s6, 3
	v_writelane_b32 v2, s7, 4
	v_readlane_b32 s4, v251, 0
	v_readlane_b32 s5, v251, 1
	s_getreg_b32 s6, hwreg(HW_REG_XCC_ID, 0, 4)
	s_load_dword s7, s[4:5], 0x100
	s_load_dwordx2 s[4:5], s[4:5], 0xf0
	v_mov_b32_e32 v0, 0x20010
	ds_read_b32 v3, v0
	ds_read_b32 v4, v0 offset:4
	ds_read_b32 v5, v0 offset:8
	s_and_b32 s6, s6, 15
	s_lshl_b32 s6, s6, 8
	v_mov_b32_e32 v8, 1
	v_mov_b32_e32 v14, 0
	s_waitcnt lgkmcnt(0)
	s_add_u32 s4, s4, 0xee42000
	s_addc_u32 s5, s5, 0
	v_mov_b32_e32 v6, s6
	v_add_u32_e32 v7, 0x400, v6
	v_add_u32_e32 v6, 0x1400, v6
	v_add_u32_e32 v13, 0x1000, v6
	v_mov_b32_e32 v15, s90
	v_and_b32_e32 v15, 7, v15
	v_lshlrev_b32_e32 v15, 8, v15
	v_cmp_ne_u32_e32 vcc, s6, v15
	s_cbranch_vccz .Lxc_ok
	v_mov_b32_e32 v15, 0x80
	global_atomic_add v15, v8, s[4:5]
.Lxc_ok:
	v_cmp_ne_u32_e32 vcc, 0, v3
	s_cbranch_vccnz .Lhb_have_1
	v_mov_b32_e32 v15, 0x400

.Lhb_done_1:
	v_mov_b32_e32 v15, 0x80
	global_load_dword v15, v15, s[4:5] sc1
	s_waitcnt vmcnt(0)
	ds_write_b32 v0, v15 offset:16
	ds_write_b32 v0, v10 offset:8
	v_readlane_b32 s4, v2, 1
	v_readlane_b32 s5, v2, 2
	v_readlane_b32 s6, v2, 3
	v_readlane_b32 s7, v2, 4
	s_waitcnt vmcnt(0) lgkmcnt(0)
	s_nop 4

.LBB0_613:
	s_and_b64 vcc, exec, s[0:1]
	s_cbranch_vccz .LBB0_630
	s_add_i32 s0, s15, s24
	s_ashr_i32 s1, s0, 31
	s_lshl_b64 s[0:1], s[0:1], 17
	s_add_u32 s0, s22, s0
	s_addc_u32 s1, s23, s1
	v_readlane_b32 s24, v254, 24
	s_add_u32 s24, s0, 0x823e000
	v_readlane_b32 s25, v254, 25
	v_readlane_b32 s26, v254, 26
	v_readlane_b32 s27, v254, 27
	s_addc_u32 s0, s1, 0
	s_and_b32 s25, s0, 0xffff
	s_mov_b32 s27, s26
	v_lshlrev_b32_e32 v4, 4, v249
	v_mov_b32_e32 v5, 0x20020
	ds_read_b32 v5, v5
	s_waitcnt lgkmcnt(0)
	v_readfirstlane_b32 s0, v5
	s_cmp_eq_u32 s0, 0
	s_cbranch_scc0 .Lg2_pub_wt
	v_cvt_pk_bf16_f32 v138, v126, v127
	v_cvt_pk_bf16_f32 v139, v128, v129
	v_cvt_pk_bf16_f32 v140, v122, v123
	v_cvt_pk_bf16_f32 v141, v124, v125
	buffer_store_dwordx4 v[138:141], v4, s[24:27], 0 offen
	v_cvt_pk_bf16_f32 v142, v114, v115
	v_cvt_pk_bf16_f32 v143, v116, v117
	v_cvt_pk_bf16_f32 v144, v106, v107
	v_cvt_pk_bf16_f32 v145, v108, v109
	s_mov_b32 s0, 0x2000
	buffer_store_dwordx4 v[142:145], v4, s[24:27], s0 offen
	v_cvt_pk_bf16_f32 v138, v98, v99
	v_cvt_pk_bf16_f32 v139, v100, v101
	v_cvt_pk_bf16_f32 v140, v90, v91
	v_cvt_pk_bf16_f32 v141, v92, v93
	s_mov_b32 s0, 0x4000
	buffer_store_dwordx4 v[138:141], v4, s[24:27], s0 offen
	v_cvt_pk_bf16_f32 v142, v82, v83
	v_cvt_pk_bf16_f32 v143, v84, v85
	v_cvt_pk_bf16_f32 v144, v74, v75
	v_cvt_pk_bf16_f32 v145, v76, v77
	s_mov_b32 s0, 0x6000
	buffer_store_dwordx4 v[142:145], v4, s[24:27], s0 offen
	v_cvt_pk_bf16_f32 v138, v118, v119
	v_cvt_pk_bf16_f32 v139, v120, v121
	v_cvt_pk_bf16_f32 v140, v110, v111
	v_cvt_pk_bf16_f32 v141, v112, v113
	s_mov_b32 s0, 0x8000
	buffer_store_dwordx4 v[138:141], v4, s[24:27], s0 offen
	v_cvt_pk_bf16_f32 v142, v102, v103
	v_cvt_pk_bf16_f32 v143, v104, v105
	v_cvt_pk_bf16_f32 v144, v94, v95
	v_cvt_pk_bf16_f32 v145, v96, v97
	s_mov_b32 s0, 0xa000
	buffer_store_dwordx4 v[142:145], v4, s[24:27], s0 offen
	v_cvt_pk_bf16_f32 v138, v86, v87
	v_cvt_pk_bf16_f32 v139, v88, v89
	v_cvt_pk_bf16_f32 v140, v78, v79
	v_cvt_pk_bf16_f32 v141, v80, v81
	s_mov_b32 s0, 0xc000
	buffer_store_dwordx4 v[138:141], v4, s[24:27], s0 offen
	v_cvt_pk_bf16_f32 v142, v70, v71
	v_cvt_pk_bf16_f32 v143, v72, v73
	v_cvt_pk_bf16_f32 v144, v66, v67
	v_cvt_pk_bf16_f32 v145, v68, v69
	s_mov_b32 s0, 0xe000
	buffer_store_dwordx4 v[142:145], v4, s[24:27], s0 offen
	v_cvt_pk_bf16_f32 v138, v62, v63
	v_cvt_pk_bf16_f32 v139, v64, v65
	v_cvt_pk_bf16_f32 v140, v58, v59
	v_cvt_pk_bf16_f32 v141, v60, v61
	s_mov_b32 s0, 0x10000
	buffer_store_dwordx4 v[138:141], v4, s[24:27], s0 offen
	v_cvt_pk_bf16_f32 v142, v50, v51
	v_cvt_pk_bf16_f32 v143, v52, v53
	v_cvt_pk_bf16_f32 v144, v42, v43
	v_cvt_pk_bf16_f32 v145, v44, v45
	s_mov_b32 s0, 0x12000
	buffer_store_dwordx4 v[142:145], v4, s[24:27], s0 offen
	v_cvt_pk_bf16_f32 v138, v34, v35
	v_cvt_pk_bf16_f32 v139, v36, v37
	v_cvt_pk_bf16_f32 v140, v26, v27
	v_cvt_pk_bf16_f32 v141, v28, v29
	s_mov_b32 s0, 0x14000
	buffer_store_dwordx4 v[138:141], v4, s[24:27], s0 offen
	v_cvt_pk_bf16_f32 v142, v18, v19
	v_cvt_pk_bf16_f32 v143, v20, v21
	v_cvt_pk_bf16_f32 v144, v136, v137
	v_cvt_pk_bf16_f32 v145, v134, v135
	s_mov_b32 s0, 0x16000
	buffer_store_dwordx4 v[142:145], v4, s[24:27], s0 offen
	v_cvt_pk_bf16_f32 v138, v54, v55
	v_cvt_pk_bf16_f32 v139, v56, v57
	v_cvt_pk_bf16_f32 v140, v46, v47
	v_cvt_pk_bf16_f32 v141, v48, v49
	s_mov_b32 s0, 0x18000
	buffer_store_dwordx4 v[138:141], v4, s[24:27], s0 offen
	v_cvt_pk_bf16_f32 v142, v38, v39
	v_cvt_pk_bf16_f32 v143, v40, v41
	v_cvt_pk_bf16_f32 v144, v30, v31
	v_cvt_pk_bf16_f32 v145, v32, v33
	s_mov_b32 s0, 0x1a000
	buffer_store_dwordx4 v[142:145], v4, s[24:27], s0 offen
	v_cvt_pk_bf16_f32 v138, v22, v23
	v_cvt_pk_bf16_f32 v139, v24, v25
	v_cvt_pk_bf16_f32 v140, v14, v15
	v_cvt_pk_bf16_f32 v141, v16, v17
	s_mov_b32 s0, 0x1c000
	buffer_store_dwordx4 v[138:141], v4, s[24:27], s0 offen
	v_cvt_pk_bf16_f32 v142, v6, v7
	v_cvt_pk_bf16_f32 v143, v8, v9
	v_cvt_pk_bf16_f32 v144, v12, v13
	v_cvt_pk_bf16_f32 v145, v10, v11
	s_mov_b32 s0, 0x1e000
	buffer_store_dwordx4 v[142:145], v4, s[24:27], s0 offen
	s_branch .Lg2_pub_done
.Lg2_pub_wt:
	v_cvt_pk_bf16_f32 v138, v126, v127
	v_cvt_pk_bf16_f32 v139, v128, v129
	v_cvt_pk_bf16_f32 v140, v122, v123
	v_cvt_pk_bf16_f32 v141, v124, v125
	buffer_store_dwordx4 v[138:141], v4, s[24:27], 0 offen sc1
	v_cvt_pk_bf16_f32 v142, v114, v115
	v_cvt_pk_bf16_f32 v143, v116, v117
	v_cvt_pk_bf16_f32 v144, v106, v107
	v_cvt_pk_bf16_f32 v145, v108, v109
	s_mov_b32 s0, 0x2000
	buffer_store_dwordx4 v[142:145], v4, s[24:27], s0 offen sc1
	v_cvt_pk_bf16_f32 v138, v98, v99
	v_cvt_pk_bf16_f32 v139, v100, v101
	v_cvt_pk_bf16_f32 v140, v90, v91
	v_cvt_pk_bf16_f32 v141, v92, v93
	s_mov_b32 s0, 0x4000
	buffer_store_dwordx4 v[138:141], v4, s[24:27], s0 offen sc1
	v_cvt_pk_bf16_f32 v142, v82, v83
	v_cvt_pk_bf16_f32 v143, v84, v85
	v_cvt_pk_bf16_f32 v144, v74, v75
	v_cvt_pk_bf16_f32 v145, v76, v77
	s_mov_b32 s0, 0x6000
	buffer_store_dwordx4 v[142:145], v4, s[24:27], s0 offen sc1
	v_cvt_pk_bf16_f32 v138, v118, v119
	v_cvt_pk_bf16_f32 v139, v120, v121
	v_cvt_pk_bf16_f32 v140, v110, v111
	v_cvt_pk_bf16_f32 v141, v112, v113
	s_mov_b32 s0, 0x8000
	buffer_store_dwordx4 v[138:141], v4, s[24:27], s0 offen sc1
	v_cvt_pk_bf16_f32 v142, v102, v103
	v_cvt_pk_bf16_f32 v143, v104, v105
	v_cvt_pk_bf16_f32 v144, v94, v95
	v_cvt_pk_bf16_f32 v145, v96, v97
	s_mov_b32 s0, 0xa000
	buffer_store_dwordx4 v[142:145], v4, s[24:27], s0 offen sc1
	v_cvt_pk_bf16_f32 v138, v86, v87
	v_cvt_pk_bf16_f32 v139, v88, v89
	v_cvt_pk_bf16_f32 v140, v78, v79
	v_cvt_pk_bf16_f32 v141, v80, v81
	s_mov_b32 s0, 0xc000
	buffer_store_dwordx4 v[138:141], v4, s[24:27], s0 offen sc1
	v_cvt_pk_bf16_f32 v142, v70, v71
	v_cvt_pk_bf16_f32 v143, v72, v73
	v_cvt_pk_bf16_f32 v144, v66, v67
	v_cvt_pk_bf16_f32 v145, v68, v69
	s_mov_b32 s0, 0xe000
	buffer_store_dwordx4 v[142:145], v4, s[24:27], s0 offen sc1
	v_cvt_pk_bf16_f32 v138, v62, v63
	v_cvt_pk_bf16_f32 v139, v64, v65
	v_cvt_pk_bf16_f32 v140, v58, v59
	v_cvt_pk_bf16_f32 v141, v60, v61
	s_mov_b32 s0, 0x10000
	buffer_store_dwordx4 v[138:141], v4, s[24:27], s0 offen sc1
	v_cvt_pk_bf16_f32 v142, v50, v51
	v_cvt_pk_bf16_f32 v143, v52, v53
	v_cvt_pk_bf16_f32 v144, v42, v43
	v_cvt_pk_bf16_f32 v145, v44, v45
	s_mov_b32 s0, 0x12000
	buffer_store_dwordx4 v[142:145], v4, s[24:27], s0 offen sc1
	v_cvt_pk_bf16_f32 v138, v34, v35
	v_cvt_pk_bf16_f32 v139, v36, v37
	v_cvt_pk_bf16_f32 v140, v26, v27
	v_cvt_pk_bf16_f32 v141, v28, v29
	s_mov_b32 s0, 0x14000
	buffer_store_dwordx4 v[138:141], v4, s[24:27], s0 offen sc1
	v_cvt_pk_bf16_f32 v142, v18, v19
	v_cvt_pk_bf16_f32 v143, v20, v21
	v_cvt_pk_bf16_f32 v144, v136, v137
	v_cvt_pk_bf16_f32 v145, v134, v135
	s_mov_b32 s0, 0x16000
	buffer_store_dwordx4 v[142:145], v4, s[24:27], s0 offen sc1
	v_cvt_pk_bf16_f32 v138, v54, v55
	v_cvt_pk_bf16_f32 v139, v56, v57
	v_cvt_pk_bf16_f32 v140, v46, v47
	v_cvt_pk_bf16_f32 v141, v48, v49
	s_mov_b32 s0, 0x18000
	buffer_store_dwordx4 v[138:141], v4, s[24:27], s0 offen sc1
	v_cvt_pk_bf16_f32 v142, v38, v39
	v_cvt_pk_bf16_f32 v143, v40, v41
	v_cvt_pk_bf16_f32 v144, v30, v31
	v_cvt_pk_bf16_f32 v145, v32, v33
	s_mov_b32 s0, 0x1a000
	buffer_store_dwordx4 v[142:145], v4, s[24:27], s0 offen sc1
	v_cvt_pk_bf16_f32 v138, v22, v23
	v_cvt_pk_bf16_f32 v139, v24, v25
	v_cvt_pk_bf16_f32 v140, v14, v15
	v_cvt_pk_bf16_f32 v141, v16, v17
	s_mov_b32 s0, 0x1c000
	buffer_store_dwordx4 v[138:141], v4, s[24:27], s0 offen sc1
	v_cvt_pk_bf16_f32 v142, v6, v7
	v_cvt_pk_bf16_f32 v143, v8, v9
	v_cvt_pk_bf16_f32 v144, v12, v13
	v_cvt_pk_bf16_f32 v145, v10, v11
	s_mov_b32 s0, 0x1e000
	buffer_store_dwordx4 v[142:145], v4, s[24:27], s0 offen sc1
.Lg2_pub_done:
	s_mov_b32 s22, s26
	v_writelane_b32 v254, s20, 24
	s_waitcnt vmcnt(0)
	s_barrier
	v_writelane_b32 v254, s21, 25
	v_writelane_b32 v254, s22, 26
	v_writelane_b32 v254, s23, 27
	s_and_saveexec_b64 s[0:1], s[4:5]
	s_cbranch_execz .LBB0_616
	s_waitcnt vmcnt(0) lgkmcnt(0)
	s_waitcnt vmcnt(0)
	v_mov_b64_e32 v[2:3], s[20:21]
	flat_atomic_add v[2:3], v237 offset:4
